# P3 epilogue rewritten: residual loads of the whole tile in flight up front (5 rolling register slots), counted vmcnt per 16-row group
# speedup vs baseline: 1.0145x; 1.0096x over previous
; #define PG8_STAGE(bufoff, gbase, voff) do { _Pragma("unroll") for (int _i = 0; _i < 2; ++_i) \
;         __builtin_amdgcn_global_load_lds((const unsigned*)((const char*)(gbase) + (voff)[_i]), (LAS unsigned*)(lds + (bufoff) + ldsw + _i * 8192), 16, 0, 0); } while (0)
; #define PG8_LDA(dst, b, h) do { _Pragma("unroll") for (int m = 0; m < 4; ++m) _Pragma("unroll") for (int k = 0; k < 2; ++k) dst[m][k] = *(const LAS bf16x8*)(lds + PG8_SA(b, h) + aoff + m * 2048 + k * 1024); } while (0)
; #define PG8_LDB(dst, b, h) do { _Pragma("unroll") for (int n = 0; n < 2; ++n) _Pragma("unroll") for (int k = 0; k < 2; ++k) dst[n][k] = *(const LAS bf16x8*)(lds + PG8_SB(b, h) + boff + n * 2048 + k * 1024); } while (0)
; #define PG8_WAIT_V(n) asm volatile("s_waitcnt vmcnt(" #n ")" ::: "memory")
; #define PG8_WAIT_L(n) asm volatile("s_waitcnt lgkmcnt(" #n ")" ::: "memory")
; #define PG8_BAR __builtin_amdgcn_s_barrier()
; #define PG8_SCHED __builtin_amdgcn_sched_barrier(0)
; template <class Epi, class Ptrs>
; __device__ __forceinline__ void gemm_phase(LAS unsigned char* lds, const int K, const StaticOrder& S, const Ptrs& P, const Epi& E) {
;     ...
;         for (int t = 0; t < nt; t += 2) {
;             const bool last = (t == nt - 2);
;             const char* a1 = cA + (size_t)(t + 1) * kstep;
;             const char* a2 = last ? nA : cA + (size_t)(t + 2) * kstep; const char* b2 = last ? nB : cB + (size_t)(t + 2) * kstep;
;             const char* a3 = a2 + kstep; const char* b3 = b2 + kstep;
;             PG8_LDB(B0, 0, 0); PG8_SCHED; PG8_LDA(At, 0, 0); PG8_STAGE(PG8_SA(1, 1), a1 + hstep, voffA);
;             PG8_WAIT_L(8); PG8_BAR; PG8_WAIT_L(0); PG8_MMA(0, 0, At, B0); PG8_BAR; PG8_SCHED;
;             PG8_LDB(B1, 0, 1); PG8_STAGE(PG8_SB(0, 0), b2, voffB);
;             PG8_BAR; PG8_WAIT_L(0); PG8_MMA(0, 1, At, B1); PG8_BAR;
;             PG8_LDA(At, 0, 1); PG8_STAGE(PG8_SA(0, 0), a2, voffA);
;             PG8_BAR; PG8_WAIT_L(0); PG8_MMA(1, 0, At, B0); PG8_BAR; PG8_SCHED;
;             PG8_STAGE(PG8_SB(0, 1), b2 + hstep, voffB);
;             PG8_WAIT_V(6); PG8_BAR; PG8_MMA(1, 1, At, B1); PG8_BAR;
;             PG8_LDB(B0, 1, 0); PG8_SCHED; PG8_LDA(At, 1, 0); PG8_STAGE(PG8_SA(0, 1), a2 + hstep, voffA);
;             PG8_WAIT_L(8); PG8_BAR; PG8_WAIT_L(0); PG8_MMA(0, 0, At, B0); PG8_BAR; PG8_SCHED;
.LBB0_353:
	ds_read_b128 v[128:131], v207
	ds_read_b128 v[132:135], v207 offset:1024
	ds_read_b128 v[136:139], v207 offset:2048
	ds_read_b128 v[140:143], v207 offset:3072
	s_add_u32 s42, s38, 0xfffc0080
	s_addc_u32 s43, s39, -1
	s_cmp_eq_u32 s41, 12
	s_cselect_b32 s45, s1, s43
	s_cselect_b32 s44, s0, s42
	s_cselect_b32 s43, s25, s23
	s_cselect_b32 s42, s24, s21
	v_lshl_add_u64 v[192:193], s[38:39], 0, v[184:185]
	s_add_i32 m0, s54, 0xc000
	ds_read_b128 v[144:147], v209
	ds_read_b128 v[148:151], v209 offset:1024
	ds_read_b128 v[152:155], v209 offset:2048
	ds_read_b128 v[156:159], v209 offset:3072
	ds_read_b128 v[160:163], v209 offset:4096
	ds_read_b128 v[164:167], v209 offset:5120
	ds_read_b128 v[168:171], v209 offset:6144
	ds_read_b128 v[172:175], v209 offset:7168
	global_load_lds_dwordx4 v[192:193], off
	v_lshl_add_u64 v[192:193], s[38:39], 0, v[186:187]
	s_add_i32 m0, s54, 0xe000
	s_nop 0
	global_load_lds_dwordx4 v[192:193], off
	s_waitcnt lgkmcnt(8)
	s_barrier
	s_waitcnt lgkmcnt(0)
	s_setprio 1
	s_waitcnt lgkmcnt(0)
	v_mfma_f32_16x16x32_bf16 v[124:127], v[128:131], v[144:147], v[124:127]
	v_mfma_f32_16x16x32_bf16 v[120:123], v[136:139], v[144:147], v[120:123]
	v_mfma_f32_16x16x32_bf16 v[108:111], v[128:131], v[152:155], v[108:111]
	v_mfma_f32_16x16x32_bf16 v[104:107], v[136:139], v[152:155], v[104:107]
	v_mfma_f32_16x16x32_bf16 v[92:95], v[128:131], v[160:163], v[92:95]
	v_mfma_f32_16x16x32_bf16 v[88:91], v[136:139], v[160:163], v[88:91]
	v_mfma_f32_16x16x32_bf16 v[76:79], v[128:131], v[168:171], v[76:79]
	v_mfma_f32_16x16x32_bf16 v[72:75], v[136:139], v[168:171], v[72:75]
	v_mfma_f32_16x16x32_bf16 v[124:127], v[132:135], v[148:151], v[124:127]
	v_mfma_f32_16x16x32_bf16 v[120:123], v[140:143], v[148:151], v[120:123]
	v_mfma_f32_16x16x32_bf16 v[108:111], v[132:135], v[156:159], v[108:111]
	v_mfma_f32_16x16x32_bf16 v[104:107], v[140:143], v[156:159], v[104:107]
	v_mfma_f32_16x16x32_bf16 v[92:95], v[132:135], v[164:167], v[92:95]
	v_mfma_f32_16x16x32_bf16 v[88:91], v[140:143], v[164:167], v[88:91]
	v_mfma_f32_16x16x32_bf16 v[76:79], v[132:135], v[172:175], v[76:79]
	v_mfma_f32_16x16x32_bf16 v[72:75], v[140:143], v[172:175], v[72:75]
	s_setprio 0
	s_barrier
	s_add_i32 s69, s66, s51
	v_lshl_add_u64 v[216:217], s[42:43], 0, v[178:179]
	s_mov_b32 m0, s69
	ds_read_b128 v[192:195], v210
	ds_read_b128 v[196:199], v210 offset:1024
	ds_read_b128 v[200:203], v210 offset:2048
	ds_read_b128 v[212:215], v210 offset:3072
	global_load_lds_dwordx4 v[216:217], off
	v_lshl_add_u64 v[218:219], s[42:43], 0, v[182:183]
	s_add_i32 m0, s69, 0x2000
	s_nop 0
	global_load_lds_dwordx4 v[218:219], off
	s_barrier
	s_waitcnt lgkmcnt(0)
	s_setprio 1
	s_waitcnt lgkmcnt(0)
	v_mfma_f32_16x16x32_bf16 v[116:119], v[192:195], v[144:147], v[116:119]
	v_mfma_f32_16x16x32_bf16 v[112:115], v[200:203], v[144:147], v[112:115]
	v_mfma_f32_16x16x32_bf16 v[100:103], v[192:195], v[152:155], v[100:103]
	v_mfma_f32_16x16x32_bf16 v[96:99], v[200:203], v[152:155], v[96:99]
	v_mfma_f32_16x16x32_bf16 v[84:87], v[192:195], v[160:163], v[84:87]
	v_mfma_f32_16x16x32_bf16 v[80:83], v[200:203], v[160:163], v[80:83]
	v_mfma_f32_16x16x32_bf16 v[68:71], v[192:195], v[168:171], v[68:71]
	v_mfma_f32_16x16x32_bf16 v[64:67], v[200:203], v[168:171], v[64:67]
	v_mfma_f32_16x16x32_bf16 v[116:119], v[196:199], v[148:151], v[116:119]
	v_mfma_f32_16x16x32_bf16 v[112:115], v[212:215], v[148:151], v[112:115]
	v_mfma_f32_16x16x32_bf16 v[100:103], v[196:199], v[156:159], v[100:103]
	v_mfma_f32_16x16x32_bf16 v[96:99], v[212:215], v[156:159], v[96:99]
	v_mfma_f32_16x16x32_bf16 v[84:87], v[196:199], v[164:167], v[84:87]
	v_mfma_f32_16x16x32_bf16 v[80:83], v[212:215], v[164:167], v[80:83]
	v_mfma_f32_16x16x32_bf16 v[68:71], v[196:199], v[172:175], v[68:71]
	v_mfma_f32_16x16x32_bf16 v[64:67], v[212:215], v[172:175], v[64:67]
	s_setprio 0
	s_mov_b32 m0, s54
	v_lshl_add_u64 v[220:221], s[44:45], 0, v[176:177]
	s_barrier
	ds_read_b128 v[144:147], v209 offset:16384
	ds_read_b128 v[148:151], v209 offset:17408
	ds_read_b128 v[152:155], v209 offset:18432
	ds_read_b128 v[156:159], v209 offset:19456
	ds_read_b128 v[160:163], v209 offset:20480
	ds_read_b128 v[164:167], v209 offset:21504
	ds_read_b128 v[168:171], v209 offset:22528
	ds_read_b128 v[172:175], v209 offset:23552
	global_load_lds_dwordx4 v[220:221], off
	v_lshl_add_u64 v[222:223], s[44:45], 0, v[180:181]
	s_mov_b32 m0, s55
	s_nop 0
	global_load_lds_dwordx4 v[222:223], off
	s_barrier
	s_waitcnt lgkmcnt(0)
	s_setprio 1
	s_waitcnt lgkmcnt(0)
	v_mfma_f32_16x16x32_bf16 v[60:63], v[128:131], v[144:147], v[60:63]
	v_mfma_f32_16x16x32_bf16 v[56:59], v[136:139], v[144:147], v[56:59]
	v_mfma_f32_16x16x32_bf16 v[44:47], v[128:131], v[152:155], v[44:47]
	v_mfma_f32_16x16x32_bf16 v[40:43], v[136:139], v[152:155], v[40:43]
	v_mfma_f32_16x16x32_bf16 v[28:31], v[128:131], v[160:163], v[28:31]
	v_mfma_f32_16x16x32_bf16 v[24:27], v[136:139], v[160:163], v[24:27]
	v_mfma_f32_16x16x32_bf16 v[12:15], v[128:131], v[168:171], v[12:15]
	v_mfma_f32_16x16x32_bf16 v[8:11], v[136:139], v[168:171], v[8:11]
	v_mfma_f32_16x16x32_bf16 v[60:63], v[132:135], v[148:151], v[60:63]
	v_mfma_f32_16x16x32_bf16 v[56:59], v[140:143], v[148:151], v[56:59]
	v_mfma_f32_16x16x32_bf16 v[44:47], v[132:135], v[156:159], v[44:47]
	v_mfma_f32_16x16x32_bf16 v[40:43], v[140:143], v[156:159], v[40:43]
	v_mfma_f32_16x16x32_bf16 v[28:31], v[132:135], v[164:167], v[28:31]
	v_mfma_f32_16x16x32_bf16 v[24:27], v[140:143], v[164:167], v[24:27]
	v_mfma_f32_16x16x32_bf16 v[12:15], v[132:135], v[172:175], v[12:15]
	v_mfma_f32_16x16x32_bf16 v[8:11], v[140:143], v[172:175], v[8:11]
	s_setprio 0
	s_barrier
; #define PG8_STAGE(bufoff, gbase, voff) do { _Pragma("unroll") for (int _i = 0; _i < 2; ++_i) \
;         __builtin_amdgcn_global_load_lds((const unsigned*)((const char*)(gbase) + (voff)[_i]), (LAS unsigned*)(lds + (bufoff) + ldsw + _i * 8192), 16, 0, 0); } while (0)
; #define PG8_LDA(dst, b, h) do { _Pragma("unroll") for (int m = 0; m < 4; ++m) _Pragma("unroll") for (int k = 0; k < 2; ++k) dst[m][k] = *(const LAS bf16x8*)(lds + PG8_SA(b, h) + aoff + m * 2048 + k * 1024); } while (0)
; #define PG8_LDB(dst, b, h) do { _Pragma("unroll") for (int n = 0; n < 2; ++n) _Pragma("unroll") for (int k = 0; k < 2; ++k) dst[n][k] = *(const LAS bf16x8*)(lds + PG8_SB(b, h) + boff + n * 2048 + k * 1024); } while (0)
; #define PG8_MMA(ai, bj, At, Bt) do { __builtin_amdgcn_s_setprio(1); _Pragma("unroll") for (int m = 0; m < 4; ++m) _Pragma("unroll") for (int n = 0; n < 2; ++n) _Pragma("unroll") for (int k = 0; k < 2; ++k) \
;         acc[ai][bj][m][n] = __builtin_amdgcn_mfma_f32_16x16x32_bf16(Bt[n][k], At[m][k], acc[ai][bj][m][n], 0, 0, 0); __builtin_amdgcn_s_setprio(0); } while (0)
; #define PG8_WAIT_V(n) asm volatile("s_waitcnt vmcnt(" #n ")" ::: "memory")
; #define PG8_WAIT_L(n) asm volatile("s_waitcnt lgkmcnt(" #n ")" ::: "memory")
; #define PG8_BAR __builtin_amdgcn_s_barrier()
; #define PG8_SCHED __builtin_amdgcn_sched_barrier(0)
; template <class Epi, class Ptrs>
; __device__ __forceinline__ void gemm_phase(LAS unsigned char* lds, const int K, const StaticOrder& S, const Ptrs& P, const Epi& E) {
;     ...
;             PG8_WAIT_V(6); PG8_BAR; PG8_MMA(1, 1, At, B1); PG8_BAR;
;             PG8_LDB(B0, 1, 0); PG8_SCHED; PG8_LDA(At, 1, 0); PG8_STAGE(PG8_SA(0, 1), a2 + hstep, voffA);
;             PG8_WAIT_L(8); PG8_BAR; PG8_WAIT_L(0); PG8_MMA(0, 0, At, B0); PG8_BAR; PG8_SCHED;
;             PG8_LDB(B1, 1, 1); PG8_STAGE(PG8_SB(1, 0), b3, voffB);
;             PG8_BAR; PG8_WAIT_L(0); PG8_MMA(0, 1, At, B1); PG8_BAR;
;             PG8_LDA(At, 1, 1); PG8_STAGE(PG8_SA(1, 0), a3, voffA);
;             PG8_BAR; PG8_WAIT_L(0); PG8_MMA(1, 0, At, B0); PG8_BAR; PG8_SCHED;
;             PG8_STAGE(PG8_SB(1, 1), b3 + hstep, voffB);
;             PG8_WAIT_V(6); PG8_BAR; PG8_MMA(1, 1, At, B1); PG8_BAR;
	s_add_u32 s70, s42, 0x40000
	s_addc_u32 s71, s43, 0
	s_add_i32 s69, s67, s51
	v_lshl_add_u64 v[128:129], s[70:71], 0, v[178:179]
	s_mov_b32 m0, s69
	s_nop 0
	global_load_lds_dwordx4 v[128:129], off
	v_lshl_add_u64 v[128:129], s[70:71], 0, v[182:183]
	s_add_i32 m0, s69, 0x2000
	s_nop 0
	global_load_lds_dwordx4 v[128:129], off
	s_waitcnt vmcnt(6)
	s_barrier
	s_setprio 1
	v_mfma_f32_16x16x32_bf16 v[52:55], v[192:195], v[144:147], v[52:55]
	v_mfma_f32_16x16x32_bf16 v[48:51], v[200:203], v[144:147], v[48:51]
	v_mfma_f32_16x16x32_bf16 v[36:39], v[192:195], v[152:155], v[36:39]
	v_mfma_f32_16x16x32_bf16 v[32:35], v[200:203], v[152:155], v[32:35]
	v_mfma_f32_16x16x32_bf16 v[20:23], v[192:195], v[160:163], v[20:23]
	v_mfma_f32_16x16x32_bf16 v[16:19], v[200:203], v[160:163], v[16:19]
	v_mfma_f32_16x16x32_bf16 v[4:7], v[192:195], v[168:171], v[4:7]
	v_mfma_f32_16x16x32_bf16 v[0:3], v[200:203], v[168:171], v[0:3]
	v_mfma_f32_16x16x32_bf16 v[52:55], v[196:199], v[148:151], v[52:55]
	v_mfma_f32_16x16x32_bf16 v[48:51], v[212:215], v[148:151], v[48:51]
	v_mfma_f32_16x16x32_bf16 v[36:39], v[196:199], v[156:159], v[36:39]
	v_mfma_f32_16x16x32_bf16 v[32:35], v[212:215], v[156:159], v[32:35]
	v_mfma_f32_16x16x32_bf16 v[20:23], v[196:199], v[164:167], v[20:23]
	v_mfma_f32_16x16x32_bf16 v[16:19], v[212:215], v[164:167], v[16:19]
	v_mfma_f32_16x16x32_bf16 v[4:7], v[196:199], v[172:175], v[4:7]
	v_mfma_f32_16x16x32_bf16 v[0:3], v[212:215], v[172:175], v[0:3]
	s_setprio 0
	s_add_i32 s69, 0, 0x18000
	v_add_u32_e32 v140, s69, v205
	s_barrier
	ds_read_b128 v[128:131], v140
	ds_read_b128 v[132:135], v140 offset:1024
	ds_read_b128 v[136:139], v140 offset:2048
	ds_read_b128 v[140:143], v140 offset:3072
	s_add_u32 s44, s44, 0x40000
	s_addc_u32 s45, s45, 0
	s_mov_b32 m0, s56
	v_lshl_add_u64 v[192:193], s[44:45], 0, v[176:177]
	ds_read_b128 v[144:147], v209 offset:32768
	ds_read_b128 v[148:151], v209 offset:33792
	ds_read_b128 v[152:155], v209 offset:34816
	ds_read_b128 v[156:159], v209 offset:35840
	ds_read_b128 v[160:163], v209 offset:36864
	ds_read_b128 v[164:167], v209 offset:37888
	ds_read_b128 v[168:171], v209 offset:38912
	ds_read_b128 v[172:175], v209 offset:39936
	global_load_lds_dwordx4 v[192:193], off
	v_lshl_add_u64 v[192:193], s[44:45], 0, v[180:181]
	s_mov_b32 m0, s57
	s_nop 0
	global_load_lds_dwordx4 v[192:193], off
	s_waitcnt lgkmcnt(8)
	s_barrier
	s_waitcnt lgkmcnt(0)
	s_setprio 1
	s_waitcnt lgkmcnt(0)
	v_mfma_f32_16x16x32_bf16 v[124:127], v[128:131], v[144:147], v[124:127]
	v_mfma_f32_16x16x32_bf16 v[120:123], v[136:139], v[144:147], v[120:123]
	v_mfma_f32_16x16x32_bf16 v[108:111], v[128:131], v[152:155], v[108:111]
	v_mfma_f32_16x16x32_bf16 v[104:107], v[136:139], v[152:155], v[104:107]
	v_mfma_f32_16x16x32_bf16 v[92:95], v[128:131], v[160:163], v[92:95]
	v_mfma_f32_16x16x32_bf16 v[88:91], v[136:139], v[160:163], v[88:91]
	v_mfma_f32_16x16x32_bf16 v[76:79], v[128:131], v[168:171], v[76:79]
	v_mfma_f32_16x16x32_bf16 v[72:75], v[136:139], v[168:171], v[72:75]
	v_mfma_f32_16x16x32_bf16 v[124:127], v[132:135], v[148:151], v[124:127]
	v_mfma_f32_16x16x32_bf16 v[120:123], v[140:143], v[148:151], v[120:123]
	v_mfma_f32_16x16x32_bf16 v[108:111], v[132:135], v[156:159], v[108:111]
	v_mfma_f32_16x16x32_bf16 v[104:107], v[140:143], v[156:159], v[104:107]
	v_mfma_f32_16x16x32_bf16 v[92:95], v[132:135], v[164:167], v[92:95]
	v_mfma_f32_16x16x32_bf16 v[88:91], v[140:143], v[164:167], v[88:91]
	v_mfma_f32_16x16x32_bf16 v[76:79], v[132:135], v[172:175], v[76:79]
	v_mfma_f32_16x16x32_bf16 v[72:75], v[140:143], v[172:175], v[72:75]
	s_setprio 0
	s_barrier
	s_add_i32 s44, 0, 0x1c000
	s_add_i32 s45, s69, s51
	v_add_u32_e32 v211, s44, v205
	v_lshl_add_u64 v[216:217], v[216:217], 0, s[18:19]
	s_mov_b32 m0, s45
	ds_read_b128 v[192:195], v211
	ds_read_b128 v[196:199], v211 offset:1024
	ds_read_b128 v[200:203], v211 offset:2048
	ds_read_b128 v[212:215], v211 offset:3072
	global_load_lds_dwordx4 v[216:217], off
	v_lshl_add_u64 v[216:217], v[218:219], 0, s[18:19]
	s_add_i32 m0, s45, 0x2000
	s_nop 0
	global_load_lds_dwordx4 v[216:217], off
	s_barrier
	s_waitcnt lgkmcnt(0)
	s_setprio 1
	s_waitcnt lgkmcnt(0)
	v_mfma_f32_16x16x32_bf16 v[116:119], v[192:195], v[144:147], v[116:119]
	v_mfma_f32_16x16x32_bf16 v[112:115], v[200:203], v[144:147], v[112:115]
	v_mfma_f32_16x16x32_bf16 v[100:103], v[192:195], v[152:155], v[100:103]
	v_mfma_f32_16x16x32_bf16 v[96:99], v[200:203], v[152:155], v[96:99]
	v_mfma_f32_16x16x32_bf16 v[84:87], v[192:195], v[160:163], v[84:87]
	v_mfma_f32_16x16x32_bf16 v[80:83], v[200:203], v[160:163], v[80:83]
	v_mfma_f32_16x16x32_bf16 v[68:71], v[192:195], v[168:171], v[68:71]
	v_mfma_f32_16x16x32_bf16 v[64:67], v[200:203], v[168:171], v[64:67]
	v_mfma_f32_16x16x32_bf16 v[116:119], v[196:199], v[148:151], v[116:119]
	v_mfma_f32_16x16x32_bf16 v[112:115], v[212:215], v[148:151], v[112:115]
	v_mfma_f32_16x16x32_bf16 v[100:103], v[196:199], v[156:159], v[100:103]
	v_mfma_f32_16x16x32_bf16 v[96:99], v[212:215], v[156:159], v[96:99]
	v_mfma_f32_16x16x32_bf16 v[84:87], v[196:199], v[164:167], v[84:87]
	v_mfma_f32_16x16x32_bf16 v[80:83], v[212:215], v[164:167], v[80:83]
	v_mfma_f32_16x16x32_bf16 v[68:71], v[196:199], v[172:175], v[68:71]
	v_mfma_f32_16x16x32_bf16 v[64:67], v[212:215], v[172:175], v[64:67]
	s_setprio 0
	s_mov_b32 m0, s63
	v_lshl_add_u64 v[216:217], v[220:221], 0, s[18:19]
	s_barrier
	ds_read_b128 v[144:147], v209 offset:49152
	ds_read_b128 v[148:151], v209 offset:50176
	ds_read_b128 v[152:155], v209 offset:51200
	ds_read_b128 v[156:159], v209 offset:52224
	ds_read_b128 v[160:163], v209 offset:53248
	ds_read_b128 v[164:167], v209 offset:54272
	ds_read_b128 v[168:171], v209 offset:55296
	ds_read_b128 v[172:175], v209 offset:56320
	global_load_lds_dwordx4 v[216:217], off
	v_lshl_add_u64 v[216:217], v[222:223], 0, s[18:19]
	s_mov_b32 m0, s64
	s_nop 0
	global_load_lds_dwordx4 v[216:217], off
	s_barrier
; __device__ __forceinline__ unsigned cvt_pk_bf16(float lo, float hi) { unsigned r; asm volatile("v_cvt_pk_bf16_f32 %0, %1, %2" : "=v"(r) : "v"(lo), "v"(hi)); return r; }
; #define PG8_STAGE(bufoff, gbase, voff) do { _Pragma("unroll") for (int _i = 0; _i < 2; ++_i) \
;         __builtin_amdgcn_global_load_lds((const unsigned*)((const char*)(gbase) + (voff)[_i]), (LAS unsigned*)(lds + (bufoff) + ldsw + _i * 8192), 16, 0, 0); } while (0)
; template <class Epi, class Ptrs>
; __device__ __forceinline__ void gemm_phase(LAS unsigned char* lds, const int K, const StaticOrder& S, const Ptrs& P, const Epi& E) {
;     ...
;             PG8_BAR; PG8_WAIT_L(0); PG8_MMA(0, 1, At, B1); PG8_BAR;
;             PG8_LDA(At, 1, 1); PG8_STAGE(PG8_SA(1, 0), a3, voffA);
;             PG8_BAR; PG8_WAIT_L(0); PG8_MMA(1, 0, At, B0); PG8_BAR; PG8_SCHED;
;             PG8_STAGE(PG8_SB(1, 1), b3 + hstep, voffB);
;             PG8_WAIT_V(6); PG8_BAR; PG8_MMA(1, 1, At, B1); PG8_BAR;
;         }
;     __device__ __forceinline__ void operator()(const f32x4 (&acc)[2][2][4][2], const Unit& u, int ui, int wr, int wc, int fr, int fq) const {
;         const int row0 = u.pm * 256 + wr * 64 + fr, col0 = u.pn * 256 + wc * 32 + 8 * fq;
;         const float* xb0 = (u.pm * 256 < MP) ? xp : xs - (size_t)MP * DM;
; #pragma unroll
;         for (int ai = 0; ai < 2; ++ai) {
;             f32x4 xv[4][2][2];
; #pragma unroll
;             for (int m = 0; m < 4; ++m)
; #pragma unroll
;                 for (int bj = 0; bj < 2; ++bj) { const float* p = xb0 + (size_t)(row0 + ai * 128 + m * 16) * DM + col0 + bj * 128; xv[m][bj][0] = *(const f32x4*)p; xv[m][bj][1] = *(const f32x4*)(p + 4); }
; #pragma unroll
;             for (int m = 0; m < 4; ++m) { const int row = row0 + ai * 128 + m * 16; const size_t off = (size_t)row * DM + col0; float ss = 0.f;
; #pragma unroll
;                 for (int bj = 0; bj < 2; ++bj) {
;                     const f32x4 v0 = acc[ai][bj][m][0] + xv[m][bj][0], v1 = acc[ai][bj][m][1] + xv[m][bj][1];
;                     u32x4 w; w.x = cvt_pk_bf16(v0[0], v0[1]); w.y = cvt_pk_bf16(v0[2], v0[3]); w.z = cvt_pk_bf16(v1[0], v1[1]); w.w = cvt_pk_bf16(v1[2], v1[3]);
;                     *(u32x4*)(xb + off + bj * 128) = w;
;                     ss += (v0[0] * v0[0] + v0[1] * v0[1]) + (v0[2] * v0[2] + v0[3] * v0[3]) + (v1[0] * v1[0] + v1[1] * v1[1]) + (v1[2] * v1[2] + v1[3] * v1[3]); }
	s_waitcnt lgkmcnt(0)
	s_setprio 1
	s_waitcnt lgkmcnt(0)
	v_mfma_f32_16x16x32_bf16 v[60:63], v[128:131], v[144:147], v[60:63]
	v_mfma_f32_16x16x32_bf16 v[56:59], v[136:139], v[144:147], v[56:59]
	v_mfma_f32_16x16x32_bf16 v[44:47], v[128:131], v[152:155], v[44:47]
	v_mfma_f32_16x16x32_bf16 v[40:43], v[136:139], v[152:155], v[40:43]
	v_mfma_f32_16x16x32_bf16 v[28:31], v[128:131], v[160:163], v[28:31]
	v_mfma_f32_16x16x32_bf16 v[24:27], v[136:139], v[160:163], v[24:27]
	v_mfma_f32_16x16x32_bf16 v[12:15], v[128:131], v[168:171], v[12:15]
	v_mfma_f32_16x16x32_bf16 v[8:11], v[136:139], v[168:171], v[8:11]
	v_mfma_f32_16x16x32_bf16 v[60:63], v[132:135], v[148:151], v[60:63]
	v_mfma_f32_16x16x32_bf16 v[56:59], v[140:143], v[148:151], v[56:59]
	v_mfma_f32_16x16x32_bf16 v[44:47], v[132:135], v[156:159], v[44:47]
	v_mfma_f32_16x16x32_bf16 v[40:43], v[140:143], v[156:159], v[40:43]
	v_mfma_f32_16x16x32_bf16 v[28:31], v[132:135], v[164:167], v[28:31]
	v_mfma_f32_16x16x32_bf16 v[24:27], v[140:143], v[164:167], v[24:27]
	v_mfma_f32_16x16x32_bf16 v[12:15], v[132:135], v[172:175], v[12:15]
	v_mfma_f32_16x16x32_bf16 v[8:11], v[140:143], v[172:175], v[8:11]
	s_setprio 0
	s_barrier
	s_add_u32 s42, s42, 0x40080
	s_addc_u32 s43, s43, 0
	s_add_i32 s44, s44, s51
	v_lshl_add_u64 v[128:129], s[42:43], 0, v[178:179]
	s_mov_b32 m0, s44
	s_nop 0
	global_load_lds_dwordx4 v[128:129], off
	v_lshl_add_u64 v[128:129], s[42:43], 0, v[182:183]
	s_add_i32 m0, s44, 0x2000
	s_nop 0
	global_load_lds_dwordx4 v[128:129], off
	s_waitcnt vmcnt(6)
	s_barrier
	s_setprio 1
	v_mfma_f32_16x16x32_bf16 v[52:55], v[192:195], v[144:147], v[52:55]
	v_mfma_f32_16x16x32_bf16 v[48:51], v[200:203], v[144:147], v[48:51]
	v_mfma_f32_16x16x32_bf16 v[36:39], v[192:195], v[152:155], v[36:39]
	v_mfma_f32_16x16x32_bf16 v[32:35], v[200:203], v[152:155], v[32:35]
	v_mfma_f32_16x16x32_bf16 v[20:23], v[192:195], v[160:163], v[20:23]
	v_mfma_f32_16x16x32_bf16 v[16:19], v[200:203], v[160:163], v[16:19]
	v_mfma_f32_16x16x32_bf16 v[4:7], v[192:195], v[168:171], v[4:7]
	v_mfma_f32_16x16x32_bf16 v[0:3], v[200:203], v[168:171], v[0:3]
	v_mfma_f32_16x16x32_bf16 v[52:55], v[196:199], v[148:151], v[52:55]
	v_mfma_f32_16x16x32_bf16 v[48:51], v[212:215], v[148:151], v[48:51]
	v_mfma_f32_16x16x32_bf16 v[36:39], v[196:199], v[156:159], v[36:39]
	v_mfma_f32_16x16x32_bf16 v[32:35], v[212:215], v[156:159], v[32:35]
	v_mfma_f32_16x16x32_bf16 v[20:23], v[196:199], v[164:167], v[20:23]
	v_mfma_f32_16x16x32_bf16 v[16:19], v[212:215], v[164:167], v[16:19]
	v_mfma_f32_16x16x32_bf16 v[4:7], v[196:199], v[172:175], v[4:7]
	v_mfma_f32_16x16x32_bf16 v[0:3], v[212:215], v[172:175], v[0:3]
	s_setprio 0
	s_add_i32 s41, s41, 2
	s_add_u32 s38, s38, 0x100
	s_addc_u32 s39, s39, 0
	s_add_u32 s21, s21, 0x100
	s_addc_u32 s23, s23, 0
	s_cmp_gt_u32 s41, 13
	s_barrier
	s_cbranch_scc0 .LBB0_353
	s_cmpk_lt_i32 s40, 0x80
	v_lshl_add_u32 v194, s40, 8, v204
	v_lshl_or_b32 v192, s12, 8, v206
	s_cselect_b32 s21, s37, s61
	s_cselect_b32 s23, s36, s60
	v_mov_b32_e32 v128, s23
	v_mov_b32_e32 v129, s21
	v_ashrrev_i32_e32 v193, 31, v192
	v_ashrrev_i32_e32 v195, 31, v194
	v_lshl_add_u64 v[196:197], v[192:193], 2, v[128:129]
	v_lshlrev_b64 v[198:199], 12, v[194:195]
	v_lshl_add_u64 v[198:199], v[196:197], 0, v[198:199]
	s_mov_b32 s73, 0
	s_mov_b32 s75, 0
	s_mov_b32 s77, 0
	global_load_dwordx4 v[128:131], v[198:199], off
	global_load_dwordx4 v[132:135], v[198:199], off offset:16
	global_load_dwordx4 v[136:139], v[198:199], off offset:512
	global_load_dwordx4 v[140:143], v[198:199], off offset:528
	v_lshlrev_b64 v[200:201], 11, v[194:195]
	v_lshl_add_u64 v[200:201], s[14:15], 0, v[200:201]
	v_lshl_add_u64 v[200:201], v[192:193], 1, v[200:201]
	s_lshl_b32 s38, s12, 2
	s_ashr_i32 s39, s38, 31
	v_lshlrev_b64 v[202:203], 6, v[194:195]
	v_lshl_add_u64 v[202:203], s[16:17], 0, v[202:203]
	v_lshl_add_u64 v[202:203], s[38:39], 2, v[202:203]
	s_lshl_b32 s12, s62, 2
	v_lshl_add_u64 v[202:203], v[202:203], 0, s[12:13]
	s_mov_b32 s76, 0x10000
	v_lshl_add_u64 v[246:247], v[198:199], 0, s[76:77]
	global_load_dwordx4 v[144:147], v[246:247], off
	global_load_dwordx4 v[148:151], v[246:247], off offset:16
	global_load_dwordx4 v[152:155], v[246:247], off offset:512
	global_load_dwordx4 v[156:159], v[246:247], off offset:528
	s_mov_b32 s76, 0x20000
	v_lshl_add_u64 v[246:247], v[198:199], 0, s[76:77]
	global_load_dwordx4 v[160:163], v[246:247], off
	global_load_dwordx4 v[164:167], v[246:247], off offset:16
	global_load_dwordx4 v[168:171], v[246:247], off offset:512
	global_load_dwordx4 v[172:175], v[246:247], off offset:528
	s_mov_b32 s76, 0x30000
	v_lshl_add_u64 v[246:247], v[198:199], 0, s[76:77]
	global_load_dwordx4 v[212:215], v[246:247], off
	global_load_dwordx4 v[216:219], v[246:247], off offset:16
	global_load_dwordx4 v[220:223], v[246:247], off offset:512
	global_load_dwordx4 v[224:227], v[246:247], off offset:528
	s_mov_b32 s76, 0x80000
	v_lshl_add_u64 v[246:247], v[198:199], 0, s[76:77]
	global_load_dwordx4 v[228:231], v[246:247], off
	global_load_dwordx4 v[232:235], v[246:247], off offset:16
	global_load_dwordx4 v[236:239], v[246:247], off offset:512
	global_load_dwordx4 v[240:243], v[246:247], off offset:528
	s_waitcnt vmcnt(16)
; __device__ __forceinline__ unsigned cvt_pk_bf16(float lo, float hi) { unsigned r; asm volatile("v_cvt_pk_bf16_f32 %0, %1, %2" : "=v"(r) : "v"(lo), "v"(hi)); return r; }
; __device__ __forceinline__ float x16_sum(float x) { auto s = __builtin_amdgcn_permlane16_swap(__float_as_uint(x), __float_as_uint(x), false, false); return __uint_as_float(s[0]) + __uint_as_float(s[1]); }
; __device__ __forceinline__ float x32_sum(float x) { auto s = __builtin_amdgcn_permlane32_swap(__float_as_uint(x), __float_as_uint(x), false, false); return __uint_as_float(s[0]) + __uint_as_float(s[1]); }
;     __device__ __forceinline__ void operator()(const f32x4 (&acc)[2][2][4][2], const Unit& u, int ui, int wr, int wc, int fr, int fq) const {
;     ...
;             for (int m = 0; m < 4; ++m) { const int row = row0 + ai * 128 + m * 16; const size_t off = (size_t)row * DM + col0; float ss = 0.f;
; #pragma unroll
;                 for (int bj = 0; bj < 2; ++bj) {
;                     const f32x4 v0 = acc[ai][bj][m][0] + xv[m][bj][0], v1 = acc[ai][bj][m][1] + xv[m][bj][1];
;                     u32x4 w; w.x = cvt_pk_bf16(v0[0], v0[1]); w.y = cvt_pk_bf16(v0[2], v0[3]); w.z = cvt_pk_bf16(v1[0], v1[1]); w.w = cvt_pk_bf16(v1[2], v1[3]);
;                     *(u32x4*)(xb + off + bj * 128) = w;
;                     ss += (v0[0] * v0[0] + v0[1] * v0[1]) + (v0[2] * v0[2] + v0[3] * v0[3]) + (v1[0] * v1[0] + v1[1] * v1[1]) + (v1[2] * v1[2] + v1[3] * v1[3]); }
;                 ss = x32_sum(x16_sum(ss));
;                 if (fq == 0) part[(size_t)row * 16 + u.pn * 4 + wc] = ss; }
	v_pk_add_f32 v[126:127], v[126:127], v[130:131]
	v_pk_add_f32 v[124:125], v[124:125], v[128:129]
	v_pk_add_f32 v[122:123], v[122:123], v[134:135]
	v_pk_add_f32 v[120:121], v[120:121], v[132:133]
	v_pk_add_f32 v[118:119], v[118:119], v[138:139]
	v_pk_add_f32 v[116:117], v[116:117], v[136:137]
	v_pk_add_f32 v[114:115], v[114:115], v[142:143]
	v_pk_add_f32 v[112:113], v[112:113], v[140:141]
	v_cvt_pk_bf16_f32 v128, v124, v125
	v_cvt_pk_bf16_f32 v129, v126, v127
	v_cvt_pk_bf16_f32 v130, v120, v121
	v_cvt_pk_bf16_f32 v131, v122, v123
	v_cvt_pk_bf16_f32 v132, v116, v117
	v_cvt_pk_bf16_f32 v133, v118, v119
	v_cvt_pk_bf16_f32 v134, v112, v113
	v_cvt_pk_bf16_f32 v135, v114, v115
	global_store_dwordx4 v[200:201], v[128:131], off
	global_store_dwordx4 v[200:201], v[132:135], off offset:256
	v_mul_f32_e32 v136, v125, v125
	v_mul_f32_e32 v137, v127, v127
	v_fmac_f32_e32 v136, v124, v124
	v_fmac_f32_e32 v137, v126, v126
	v_add_f32_e32 v136, v136, v137
	v_mul_f32_e32 v137, v121, v121
	v_fmac_f32_e32 v137, v120, v120
	v_add_f32_e32 v136, v136, v137
	v_mul_f32_e32 v137, v123, v123
	v_fmac_f32_e32 v137, v122, v122
	v_add_f32_e32 v138, v137, v136
	v_mul_f32_e32 v136, v117, v117
	v_mul_f32_e32 v137, v119, v119
	v_fmac_f32_e32 v136, v116, v116
	v_fmac_f32_e32 v137, v118, v118
	v_add_f32_e32 v136, v136, v137
	v_mul_f32_e32 v137, v113, v113
	v_fmac_f32_e32 v137, v112, v112
	v_add_f32_e32 v136, v136, v137
	v_mul_f32_e32 v137, v115, v115
	v_fmac_f32_e32 v137, v114, v114
	v_add_f32_e32 v136, v137, v136
	v_add_f32_e32 v136, v138, v136
	v_mov_b32_e32 v137, v136
	s_nop 1
	v_permlane16_swap_b32_e32 v136, v137
	v_add_f32_e32 v136, v136, v137
	v_mov_b32_e32 v137, v136
	s_nop 1
	v_permlane32_swap_b32_e32 v136, v137
	s_and_saveexec_b64 s[40:41], s[6:7]
	v_add_f32_e32 v136, v136, v137
	global_store_dword v[202:203], v136, off
	s_or_b64 exec, exec, s[40:41]
	s_mov_b32 s76, 0x90000
	v_lshl_add_u64 v[246:247], v[198:199], 0, s[76:77]
	global_load_dwordx4 v[128:131], v[246:247], off
	global_load_dwordx4 v[132:135], v[246:247], off offset:16
	global_load_dwordx4 v[136:139], v[246:247], off offset:512
	global_load_dwordx4 v[140:143], v[246:247], off offset:528
	s_waitcnt vmcnt(19)
	v_pk_add_f32 v[110:111], v[110:111], v[146:147]
	v_pk_add_f32 v[108:109], v[108:109], v[144:145]
	v_pk_add_f32 v[106:107], v[106:107], v[150:151]
	v_pk_add_f32 v[104:105], v[104:105], v[148:149]
	v_pk_add_f32 v[102:103], v[102:103], v[154:155]
	v_pk_add_f32 v[100:101], v[100:101], v[152:153]
	v_pk_add_f32 v[98:99], v[98:99], v[158:159]
	v_pk_add_f32 v[96:97], v[96:97], v[156:157]
	v_cvt_pk_bf16_f32 v144, v108, v109
	v_cvt_pk_bf16_f32 v145, v110, v111
	v_cvt_pk_bf16_f32 v146, v104, v105
	v_cvt_pk_bf16_f32 v147, v106, v107
	v_cvt_pk_bf16_f32 v148, v100, v101
	v_cvt_pk_bf16_f32 v149, v102, v103
	v_cvt_pk_bf16_f32 v150, v96, v97
	v_cvt_pk_bf16_f32 v151, v98, v99
	s_mov_b32 s72, 0x8000
	v_lshl_add_u64 v[244:245], v[200:201], 0, s[72:73]
	global_store_dwordx4 v[244:245], v[144:147], off
	global_store_dwordx4 v[244:245], v[148:151], off offset:256
	v_mul_f32_e32 v152, v109, v109
	v_mul_f32_e32 v153, v111, v111
	v_fmac_f32_e32 v152, v108, v108
	v_fmac_f32_e32 v153, v110, v110
	v_add_f32_e32 v152, v152, v153
	v_mul_f32_e32 v153, v105, v105
	v_fmac_f32_e32 v153, v104, v104
	v_add_f32_e32 v152, v152, v153
	v_mul_f32_e32 v153, v107, v107
	v_fmac_f32_e32 v153, v106, v106
	v_add_f32_e32 v154, v153, v152
	v_mul_f32_e32 v152, v101, v101
	v_mul_f32_e32 v153, v103, v103
	v_fmac_f32_e32 v152, v100, v100
	v_fmac_f32_e32 v153, v102, v102
	v_add_f32_e32 v152, v152, v153
	v_mul_f32_e32 v153, v97, v97
	v_fmac_f32_e32 v153, v96, v96
	v_add_f32_e32 v152, v152, v153
	v_mul_f32_e32 v153, v99, v99
	v_fmac_f32_e32 v153, v98, v98
	v_add_f32_e32 v152, v153, v152
	v_add_f32_e32 v152, v154, v152
	v_mov_b32_e32 v153, v152
	s_nop 1
	v_permlane16_swap_b32_e32 v152, v153
	v_add_f32_e32 v152, v152, v153
	v_mov_b32_e32 v153, v152
	s_nop 1
	v_permlane32_swap_b32_e32 v152, v153
	s_and_saveexec_b64 s[40:41], s[6:7]
	s_mov_b32 s74, 0x400
	v_lshl_add_u64 v[244:245], v[202:203], 0, s[74:75]
	v_add_f32_e32 v152, v152, v153
	global_store_dword v[244:245], v152, off
	s_or_b64 exec, exec, s[40:41]
	s_mov_b32 s76, 0xa0000
	v_lshl_add_u64 v[246:247], v[198:199], 0, s[76:77]
	global_load_dwordx4 v[144:147], v[246:247], off
	global_load_dwordx4 v[148:151], v[246:247], off offset:16
	global_load_dwordx4 v[152:155], v[246:247], off offset:512
	global_load_dwordx4 v[156:159], v[246:247], off offset:528
	s_waitcnt vmcnt(22)
	v_pk_add_f32 v[94:95], v[94:95], v[162:163]
	v_pk_add_f32 v[92:93], v[92:93], v[160:161]
	v_pk_add_f32 v[90:91], v[90:91], v[166:167]
	v_pk_add_f32 v[88:89], v[88:89], v[164:165]
	v_pk_add_f32 v[86:87], v[86:87], v[170:171]
	v_pk_add_f32 v[84:85], v[84:85], v[168:169]
	v_pk_add_f32 v[82:83], v[82:83], v[174:175]
	v_pk_add_f32 v[80:81], v[80:81], v[172:173]
	v_cvt_pk_bf16_f32 v160, v92, v93
	v_cvt_pk_bf16_f32 v161, v94, v95
	v_cvt_pk_bf16_f32 v162, v88, v89
	v_cvt_pk_bf16_f32 v163, v90, v91
	v_cvt_pk_bf16_f32 v164, v84, v85
	v_cvt_pk_bf16_f32 v165, v86, v87
	v_cvt_pk_bf16_f32 v166, v80, v81
	v_cvt_pk_bf16_f32 v167, v82, v83
	s_mov_b32 s72, 0x10000
	v_lshl_add_u64 v[244:245], v[200:201], 0, s[72:73]
	global_store_dwordx4 v[244:245], v[160:163], off
	global_store_dwordx4 v[244:245], v[164:167], off offset:256
	v_mul_f32_e32 v168, v93, v93
	v_mul_f32_e32 v169, v95, v95
	v_fmac_f32_e32 v168, v92, v92
	v_fmac_f32_e32 v169, v94, v94
	v_add_f32_e32 v168, v168, v169
	v_mul_f32_e32 v169, v89, v89
	v_fmac_f32_e32 v169, v88, v88
	v_add_f32_e32 v168, v168, v169
	v_mul_f32_e32 v169, v91, v91
	v_fmac_f32_e32 v169, v90, v90
	v_add_f32_e32 v170, v169, v168
	v_mul_f32_e32 v168, v85, v85
	v_mul_f32_e32 v169, v87, v87
	v_fmac_f32_e32 v168, v84, v84
	v_fmac_f32_e32 v169, v86, v86
	v_add_f32_e32 v168, v168, v169
	v_mul_f32_e32 v169, v81, v81
	v_fmac_f32_e32 v169, v80, v80
	v_add_f32_e32 v168, v168, v169
	v_mul_f32_e32 v169, v83, v83
	v_fmac_f32_e32 v169, v82, v82
	v_add_f32_e32 v168, v169, v168
	v_add_f32_e32 v168, v170, v168
	v_mov_b32_e32 v169, v168
	s_nop 1
	v_permlane16_swap_b32_e32 v168, v169
	v_add_f32_e32 v168, v168, v169
	v_mov_b32_e32 v169, v168
	s_nop 1
	v_permlane32_swap_b32_e32 v168, v169
	s_and_saveexec_b64 s[40:41], s[6:7]
	s_mov_b32 s74, 0x800
	v_lshl_add_u64 v[244:245], v[202:203], 0, s[74:75]
	v_add_f32_e32 v168, v168, v169
	global_store_dword v[244:245], v168, off
	s_or_b64 exec, exec, s[40:41]
	s_mov_b32 s76, 0xb0000
	v_lshl_add_u64 v[246:247], v[198:199], 0, s[76:77]
	global_load_dwordx4 v[160:163], v[246:247], off
	global_load_dwordx4 v[164:167], v[246:247], off offset:16
	global_load_dwordx4 v[168:171], v[246:247], off offset:512
	global_load_dwordx4 v[172:175], v[246:247], off offset:528
	s_waitcnt vmcnt(25)
; __device__ __forceinline__ unsigned cvt_pk_bf16(float lo, float hi) { unsigned r; asm volatile("v_cvt_pk_bf16_f32 %0, %1, %2" : "=v"(r) : "v"(lo), "v"(hi)); return r; }
; __device__ __forceinline__ float x16_sum(float x) { auto s = __builtin_amdgcn_permlane16_swap(__float_as_uint(x), __float_as_uint(x), false, false); return __uint_as_float(s[0]) + __uint_as_float(s[1]); }
; __device__ __forceinline__ float x32_sum(float x) { auto s = __builtin_amdgcn_permlane32_swap(__float_as_uint(x), __float_as_uint(x), false, false); return __uint_as_float(s[0]) + __uint_as_float(s[1]); }
;     __device__ __forceinline__ void operator()(const f32x4 (&acc)[2][2][4][2], const Unit& u, int ui, int wr, int wc, int fr, int fq) const {
;     ...
;             for (int m = 0; m < 4; ++m) { const int row = row0 + ai * 128 + m * 16; const size_t off = (size_t)row * DM + col0; float ss = 0.f;
; #pragma unroll
;                 for (int bj = 0; bj < 2; ++bj) {
;                     const f32x4 v0 = acc[ai][bj][m][0] + xv[m][bj][0], v1 = acc[ai][bj][m][1] + xv[m][bj][1];
;                     u32x4 w; w.x = cvt_pk_bf16(v0[0], v0[1]); w.y = cvt_pk_bf16(v0[2], v0[3]); w.z = cvt_pk_bf16(v1[0], v1[1]); w.w = cvt_pk_bf16(v1[2], v1[3]);
;                     *(u32x4*)(xb + off + bj * 128) = w;
;                     ss += (v0[0] * v0[0] + v0[1] * v0[1]) + (v0[2] * v0[2] + v0[3] * v0[3]) + (v1[0] * v1[0] + v1[1] * v1[1]) + (v1[2] * v1[2] + v1[3] * v1[3]); }
;                 ss = x32_sum(x16_sum(ss));
;                 if (fq == 0) part[(size_t)row * 16 + u.pn * 4 + wc] = ss; }
	v_pk_add_f32 v[78:79], v[78:79], v[214:215]
	v_pk_add_f32 v[76:77], v[76:77], v[212:213]
	v_pk_add_f32 v[74:75], v[74:75], v[218:219]
	v_pk_add_f32 v[72:73], v[72:73], v[216:217]
	v_pk_add_f32 v[70:71], v[70:71], v[222:223]
	v_pk_add_f32 v[68:69], v[68:69], v[220:221]
	v_pk_add_f32 v[66:67], v[66:67], v[226:227]
	v_pk_add_f32 v[64:65], v[64:65], v[224:225]
	v_cvt_pk_bf16_f32 v212, v76, v77
	v_cvt_pk_bf16_f32 v213, v78, v79
	v_cvt_pk_bf16_f32 v214, v72, v73
	v_cvt_pk_bf16_f32 v215, v74, v75
	v_cvt_pk_bf16_f32 v216, v68, v69
	v_cvt_pk_bf16_f32 v217, v70, v71
	v_cvt_pk_bf16_f32 v218, v64, v65
	v_cvt_pk_bf16_f32 v219, v66, v67
	s_mov_b32 s72, 0x18000
	v_lshl_add_u64 v[244:245], v[200:201], 0, s[72:73]
	global_store_dwordx4 v[244:245], v[212:215], off
	global_store_dwordx4 v[244:245], v[216:219], off offset:256
	v_mul_f32_e32 v220, v77, v77
	v_mul_f32_e32 v221, v79, v79
	v_fmac_f32_e32 v220, v76, v76
	v_fmac_f32_e32 v221, v78, v78
	v_add_f32_e32 v220, v220, v221
	v_mul_f32_e32 v221, v73, v73
	v_fmac_f32_e32 v221, v72, v72
	v_add_f32_e32 v220, v220, v221
	v_mul_f32_e32 v221, v75, v75
	v_fmac_f32_e32 v221, v74, v74
	v_add_f32_e32 v222, v221, v220
	v_mul_f32_e32 v220, v69, v69
	v_mul_f32_e32 v221, v71, v71
	v_fmac_f32_e32 v220, v68, v68
	v_fmac_f32_e32 v221, v70, v70
	v_add_f32_e32 v220, v220, v221
	v_mul_f32_e32 v221, v65, v65
	v_fmac_f32_e32 v221, v64, v64
	v_add_f32_e32 v220, v220, v221
	v_mul_f32_e32 v221, v67, v67
	v_fmac_f32_e32 v221, v66, v66
	v_add_f32_e32 v220, v221, v220
	v_add_f32_e32 v220, v222, v220
	v_mov_b32_e32 v221, v220
	s_nop 1
	v_permlane16_swap_b32_e32 v220, v221
	v_add_f32_e32 v220, v220, v221
	v_mov_b32_e32 v221, v220
	s_nop 1
	v_permlane32_swap_b32_e32 v220, v221
	s_and_saveexec_b64 s[40:41], s[6:7]
	s_mov_b32 s74, 0xc00
	v_lshl_add_u64 v[244:245], v[202:203], 0, s[74:75]
	v_add_f32_e32 v220, v220, v221
	global_store_dword v[244:245], v220, off
	s_or_b64 exec, exec, s[40:41]
	s_waitcnt vmcnt(24)
	v_pk_add_f32 v[62:63], v[62:63], v[230:231]
	v_pk_add_f32 v[60:61], v[60:61], v[228:229]
	v_pk_add_f32 v[58:59], v[58:59], v[234:235]
	v_pk_add_f32 v[56:57], v[56:57], v[232:233]
	v_pk_add_f32 v[54:55], v[54:55], v[238:239]
	v_pk_add_f32 v[52:53], v[52:53], v[236:237]
	v_pk_add_f32 v[50:51], v[50:51], v[242:243]
	v_pk_add_f32 v[48:49], v[48:49], v[240:241]
	v_cvt_pk_bf16_f32 v228, v60, v61
	v_cvt_pk_bf16_f32 v229, v62, v63
	v_cvt_pk_bf16_f32 v230, v56, v57
	v_cvt_pk_bf16_f32 v231, v58, v59
	v_cvt_pk_bf16_f32 v232, v52, v53
	v_cvt_pk_bf16_f32 v233, v54, v55
	v_cvt_pk_bf16_f32 v234, v48, v49
	v_cvt_pk_bf16_f32 v235, v50, v51
	s_mov_b32 s72, 0x40000
	v_lshl_add_u64 v[244:245], v[200:201], 0, s[72:73]
	global_store_dwordx4 v[244:245], v[228:231], off
	global_store_dwordx4 v[244:245], v[232:235], off offset:256
	v_mul_f32_e32 v236, v61, v61
	v_mul_f32_e32 v237, v63, v63
	v_fmac_f32_e32 v236, v60, v60
	v_fmac_f32_e32 v237, v62, v62
	v_add_f32_e32 v236, v236, v237
	v_mul_f32_e32 v237, v57, v57
	v_fmac_f32_e32 v237, v56, v56
	v_add_f32_e32 v236, v236, v237
	v_mul_f32_e32 v237, v59, v59
	v_fmac_f32_e32 v237, v58, v58
	v_add_f32_e32 v238, v237, v236
	v_mul_f32_e32 v236, v53, v53
	v_mul_f32_e32 v237, v55, v55
	v_fmac_f32_e32 v236, v52, v52
	v_fmac_f32_e32 v237, v54, v54
	v_add_f32_e32 v236, v236, v237
	v_mul_f32_e32 v237, v49, v49
	v_fmac_f32_e32 v237, v48, v48
	v_add_f32_e32 v236, v236, v237
	v_mul_f32_e32 v237, v51, v51
	v_fmac_f32_e32 v237, v50, v50
	v_add_f32_e32 v236, v237, v236
	v_add_f32_e32 v236, v238, v236
	v_mov_b32_e32 v237, v236
	s_nop 1
	v_permlane16_swap_b32_e32 v236, v237
	v_add_f32_e32 v236, v236, v237
	v_mov_b32_e32 v237, v236
	s_nop 1
	v_permlane32_swap_b32_e32 v236, v237
	s_and_saveexec_b64 s[40:41], s[6:7]
	s_mov_b32 s74, 0x2000
	v_lshl_add_u64 v[244:245], v[202:203], 0, s[74:75]
	v_add_f32_e32 v236, v236, v237
	global_store_dword v[244:245], v236, off
	s_or_b64 exec, exec, s[40:41]
	s_waitcnt vmcnt(20)
	v_pk_add_f32 v[46:47], v[46:47], v[130:131]
	v_pk_add_f32 v[44:45], v[44:45], v[128:129]
	v_pk_add_f32 v[42:43], v[42:43], v[134:135]
	v_pk_add_f32 v[40:41], v[40:41], v[132:133]
	v_pk_add_f32 v[38:39], v[38:39], v[138:139]
	v_pk_add_f32 v[36:37], v[36:37], v[136:137]
	v_pk_add_f32 v[34:35], v[34:35], v[142:143]
	v_pk_add_f32 v[32:33], v[32:33], v[140:141]
	v_cvt_pk_bf16_f32 v128, v44, v45
	v_cvt_pk_bf16_f32 v129, v46, v47
	v_cvt_pk_bf16_f32 v130, v40, v41
	v_cvt_pk_bf16_f32 v131, v42, v43
	v_cvt_pk_bf16_f32 v132, v36, v37
	v_cvt_pk_bf16_f32 v133, v38, v39
	v_cvt_pk_bf16_f32 v134, v32, v33
	v_cvt_pk_bf16_f32 v135, v34, v35
	s_mov_b32 s72, 0x48000
	v_lshl_add_u64 v[244:245], v[200:201], 0, s[72:73]
	global_store_dwordx4 v[244:245], v[128:131], off
	global_store_dwordx4 v[244:245], v[132:135], off offset:256
	v_mul_f32_e32 v136, v45, v45
	v_mul_f32_e32 v137, v47, v47
	v_fmac_f32_e32 v136, v44, v44
	v_fmac_f32_e32 v137, v46, v46
	v_add_f32_e32 v136, v136, v137
	v_mul_f32_e32 v137, v41, v41
	v_fmac_f32_e32 v137, v40, v40
	v_add_f32_e32 v136, v136, v137
	v_mul_f32_e32 v137, v43, v43
	v_fmac_f32_e32 v137, v42, v42
	v_add_f32_e32 v138, v137, v136
	v_mul_f32_e32 v136, v37, v37
	v_mul_f32_e32 v137, v39, v39
	v_fmac_f32_e32 v136, v36, v36
	v_fmac_f32_e32 v137, v38, v38
	v_add_f32_e32 v136, v136, v137
	v_mul_f32_e32 v137, v33, v33
	v_fmac_f32_e32 v137, v32, v32
	v_add_f32_e32 v136, v136, v137
	v_mul_f32_e32 v137, v35, v35
	v_fmac_f32_e32 v137, v34, v34
	v_add_f32_e32 v136, v137, v136
	v_add_f32_e32 v136, v138, v136
	v_mov_b32_e32 v137, v136
	s_nop 1
	v_permlane16_swap_b32_e32 v136, v137
	v_add_f32_e32 v136, v136, v137
	v_mov_b32_e32 v137, v136
	s_nop 1
	v_permlane32_swap_b32_e32 v136, v137
	s_and_saveexec_b64 s[40:41], s[6:7]
	s_mov_b32 s74, 0x2400
	v_lshl_add_u64 v[244:245], v[202:203], 0, s[74:75]
	v_add_f32_e32 v136, v136, v137
	global_store_dword v[244:245], v136, off
	s_or_b64 exec, exec, s[40:41]
	s_waitcnt vmcnt(16)
; __device__ __forceinline__ unsigned cvt_pk_bf16(float lo, float hi) { unsigned r; asm volatile("v_cvt_pk_bf16_f32 %0, %1, %2" : "=v"(r) : "v"(lo), "v"(hi)); return r; }
; __device__ __forceinline__ float x16_sum(float x) { auto s = __builtin_amdgcn_permlane16_swap(__float_as_uint(x), __float_as_uint(x), false, false); return __uint_as_float(s[0]) + __uint_as_float(s[1]); }
; __device__ __forceinline__ float x32_sum(float x) { auto s = __builtin_amdgcn_permlane32_swap(__float_as_uint(x), __float_as_uint(x), false, false); return __uint_as_float(s[0]) + __uint_as_float(s[1]); }
; #define PG8_WAIT_V(n) asm volatile("s_waitcnt vmcnt(" #n ")" ::: "memory")
; #define PG8_BAR __builtin_amdgcn_s_barrier()
; template <class Epi, class Ptrs>
; __device__ __forceinline__ void gemm_phase(LAS unsigned char* lds, const int K, const StaticOrder& S, const Ptrs& P, const Epi& E) {
;     ...
;     PG8_WAIT_V(0);
;     if (wr == 0) PG8_BAR;
;     __device__ __forceinline__ void operator()(const f32x4 (&acc)[2][2][4][2], const Unit& u, int ui, int wr, int wc, int fr, int fq) const {
;     ...
;             for (int m = 0; m < 4; ++m) { const int row = row0 + ai * 128 + m * 16; const size_t off = (size_t)row * DM + col0; float ss = 0.f;
; #pragma unroll
;                 for (int bj = 0; bj < 2; ++bj) {
;                     const f32x4 v0 = acc[ai][bj][m][0] + xv[m][bj][0], v1 = acc[ai][bj][m][1] + xv[m][bj][1];
;                     u32x4 w; w.x = cvt_pk_bf16(v0[0], v0[1]); w.y = cvt_pk_bf16(v0[2], v0[3]); w.z = cvt_pk_bf16(v1[0], v1[1]); w.w = cvt_pk_bf16(v1[2], v1[3]);
;                     *(u32x4*)(xb + off + bj * 128) = w;
;                     ss += (v0[0] * v0[0] + v0[1] * v0[1]) + (v0[2] * v0[2] + v0[3] * v0[3]) + (v1[0] * v1[0] + v1[1] * v1[1]) + (v1[2] * v1[2] + v1[3] * v1[3]); }
;                 ss = x32_sum(x16_sum(ss));
;                 if (fq == 0) part[(size_t)row * 16 + u.pn * 4 + wc] = ss; }
	v_pk_add_f32 v[30:31], v[30:31], v[146:147]
	v_pk_add_f32 v[28:29], v[28:29], v[144:145]
	v_pk_add_f32 v[26:27], v[26:27], v[150:151]
	v_pk_add_f32 v[24:25], v[24:25], v[148:149]
	v_pk_add_f32 v[22:23], v[22:23], v[154:155]
	v_pk_add_f32 v[20:21], v[20:21], v[152:153]
	v_pk_add_f32 v[18:19], v[18:19], v[158:159]
	v_pk_add_f32 v[16:17], v[16:17], v[156:157]
	v_cvt_pk_bf16_f32 v144, v28, v29
	v_cvt_pk_bf16_f32 v145, v30, v31
	v_cvt_pk_bf16_f32 v146, v24, v25
	v_cvt_pk_bf16_f32 v147, v26, v27
	v_cvt_pk_bf16_f32 v148, v20, v21
	v_cvt_pk_bf16_f32 v149, v22, v23
	v_cvt_pk_bf16_f32 v150, v16, v17
	v_cvt_pk_bf16_f32 v151, v18, v19
	s_mov_b32 s72, 0x50000
	v_lshl_add_u64 v[244:245], v[200:201], 0, s[72:73]
	global_store_dwordx4 v[244:245], v[144:147], off
	global_store_dwordx4 v[244:245], v[148:151], off offset:256
	v_mul_f32_e32 v152, v29, v29
	v_mul_f32_e32 v153, v31, v31
	v_fmac_f32_e32 v152, v28, v28
	v_fmac_f32_e32 v153, v30, v30
	v_add_f32_e32 v152, v152, v153
	v_mul_f32_e32 v153, v25, v25
	v_fmac_f32_e32 v153, v24, v24
	v_add_f32_e32 v152, v152, v153
	v_mul_f32_e32 v153, v27, v27
	v_fmac_f32_e32 v153, v26, v26
	v_add_f32_e32 v154, v153, v152
	v_mul_f32_e32 v152, v21, v21
	v_mul_f32_e32 v153, v23, v23
	v_fmac_f32_e32 v152, v20, v20
	v_fmac_f32_e32 v153, v22, v22
	v_add_f32_e32 v152, v152, v153
	v_mul_f32_e32 v153, v17, v17
	v_fmac_f32_e32 v153, v16, v16
	v_add_f32_e32 v152, v152, v153
	v_mul_f32_e32 v153, v19, v19
	v_fmac_f32_e32 v153, v18, v18
	v_add_f32_e32 v152, v153, v152
	v_add_f32_e32 v152, v154, v152
	v_mov_b32_e32 v153, v152
	s_nop 1
	v_permlane16_swap_b32_e32 v152, v153
	v_add_f32_e32 v152, v152, v153
	v_mov_b32_e32 v153, v152
	s_nop 1
	v_permlane32_swap_b32_e32 v152, v153
	s_and_saveexec_b64 s[40:41], s[6:7]
	s_mov_b32 s74, 0x2800
	v_lshl_add_u64 v[244:245], v[202:203], 0, s[74:75]
	v_add_f32_e32 v152, v152, v153
	global_store_dword v[244:245], v152, off
	s_or_b64 exec, exec, s[40:41]
	s_waitcnt vmcnt(12)
	v_pk_add_f32 v[14:15], v[14:15], v[162:163]
	v_pk_add_f32 v[12:13], v[12:13], v[160:161]
	v_pk_add_f32 v[10:11], v[10:11], v[166:167]
	v_pk_add_f32 v[8:9], v[8:9], v[164:165]
	v_pk_add_f32 v[6:7], v[6:7], v[170:171]
	v_pk_add_f32 v[4:5], v[4:5], v[168:169]
	v_pk_add_f32 v[2:3], v[2:3], v[174:175]
	v_pk_add_f32 v[0:1], v[0:1], v[172:173]
	v_cvt_pk_bf16_f32 v160, v12, v13
	v_cvt_pk_bf16_f32 v161, v14, v15
	v_cvt_pk_bf16_f32 v162, v8, v9
	v_cvt_pk_bf16_f32 v163, v10, v11
	v_cvt_pk_bf16_f32 v164, v4, v5
	v_cvt_pk_bf16_f32 v165, v6, v7
	v_cvt_pk_bf16_f32 v166, v0, v1
	v_cvt_pk_bf16_f32 v167, v2, v3
	s_mov_b32 s72, 0x58000
	v_lshl_add_u64 v[244:245], v[200:201], 0, s[72:73]
	global_store_dwordx4 v[244:245], v[160:163], off
	global_store_dwordx4 v[244:245], v[164:167], off offset:256
	v_mul_f32_e32 v168, v13, v13
	v_mul_f32_e32 v169, v15, v15
	v_fmac_f32_e32 v168, v12, v12
	v_fmac_f32_e32 v169, v14, v14
	v_add_f32_e32 v168, v168, v169
	v_mul_f32_e32 v169, v9, v9
	v_fmac_f32_e32 v169, v8, v8
	v_add_f32_e32 v168, v168, v169
	v_mul_f32_e32 v169, v11, v11
	v_fmac_f32_e32 v169, v10, v10
	v_add_f32_e32 v170, v169, v168
	v_mul_f32_e32 v168, v5, v5
	v_mul_f32_e32 v169, v7, v7
	v_fmac_f32_e32 v168, v4, v4
	v_fmac_f32_e32 v169, v6, v6
	v_add_f32_e32 v168, v168, v169
	v_mul_f32_e32 v169, v1, v1
	v_fmac_f32_e32 v169, v0, v0
	v_add_f32_e32 v168, v168, v169
	v_mul_f32_e32 v169, v3, v3
	v_fmac_f32_e32 v169, v2, v2
	v_add_f32_e32 v168, v169, v168
	v_add_f32_e32 v168, v170, v168
	v_mov_b32_e32 v169, v168
	s_nop 1
	v_permlane16_swap_b32_e32 v168, v169
	v_add_f32_e32 v168, v168, v169
	v_mov_b32_e32 v169, v168
	s_nop 1
	v_permlane32_swap_b32_e32 v168, v169
	s_and_saveexec_b64 s[40:41], s[6:7]
	s_mov_b32 s74, 0x2c00
	v_lshl_add_u64 v[244:245], v[202:203], 0, s[74:75]
	v_add_f32_e32 v168, v168, v169
	global_store_dword v[244:245], v168, off
	s_or_b64 exec, exec, s[40:41]
	s_branch .LBB0_347
.LBB0_370:
	s_nop 0
	s_nop 0
	s_nop 0
	s_nop 0
	s_nop 0
	s_nop 0
	s_nop 0
	s_nop 0
	s_nop 0
	s_nop 0
	s_nop 0
	s_nop 0
	s_nop 0
	s_nop 0
	s_nop 0
	s_nop 0
	s_nop 0
	s_nop 0
	s_nop 0
	s_nop 0
	s_nop 0
	s_nop 0
	s_nop 0
	s_waitcnt vmcnt(0)
	s_cmpk_gt_u32 s46, 0xff
	s_cbranch_scc1 .LBB0_372
	s_barrier
